# P3 task prologue: wave 4 issues its eight k-row sumsq loads together before the row DMAs (was 8 serial vmcnt(0) round trips); plus earlier edits
# speedup vs baseline: 1.0041x; 1.0022x over previous
; __global__ void __launch_bounds__(NWAVES * 64, 2) fwd(Args a) {
;     ...
;             if (grp < 2) { b = 4 * grp + (task >> 4); h = (task >> 1) & 7; r0 = (task & 1) * 16; rows = 32; }
;             else { b = 8 + (grp - 2); h = task >> 3; r0 = (task & 7) * 16; rows = 128; }
;             const int base = b < 8 ? b * 2048 : NPR + (b - 8) * 8192;
;             const int gbase = base - GROWS * grp;
;             __syncthreads();
;             { const int dr = tid >> 5, dc = tid & 31; tbl[tid] = (dr < 15 && dc < 31) ? a.in[I_RPB][h * 465 + dr * 31 + dc] * 1.4426950408889634f : -1e30f; }
;             if (tid < 64) qgt[tid] = a.in[I_QNG][tid] * a.in[I_KNG][tid];
;             bool sel[4]; int dsel[4]; unsigned psel[2];
;             { const int qc = 16 * j + l15, cs = min(max(qc - 8, 0), 48), o = cs - kc0;
; #pragma unroll
;               for (int e = 0; e < 4; ++e) { const int pp = 4 * fq + e; sel[e] = pp < o; dsel[e] = 4 * (kc0 + pp + (sel[e] ? 16 : 0) - qc + 15); }
;               psel[0] = (sel[0] ? 0u : 0xFFFFu) | (sel[1] ? 0u : 0xFFFF0000u); psel[1] = (sel[2] ? 0u : 0xFFFFu) | (sel[3] ? 0u : 0xFFFF0000u); }
;             const int koff0 = l15 * 128 + 16 * (fq ^ (l15 & 7)), koff1 = l15 * 128 + 16 * ((fq ^ (l15 & 7)) ^ 4);
;             int voff[4];
; #pragma unroll
;             for (int db = 0; db < 4; ++db) voff[db] = (4 * fq + tq) * 128 + 16 * ((2 * db + (tp >> 1)) ^ (4 * (fq & 1) + tq)) + 8 * (tp & 1);
;     ...
;             { const int lo0 = min(max(r0 - 4, 0), rows - 8);
;               for (int kr = lo0; kr < lo0 + 8; ++kr) STAGE_ROW(kr); }
.LBB0_238:
	s_or_b64 exec, exec, s[12:13]
	s_lshl_b32 s12, s33, 4
	s_lshl_b32 s13, s22, 13
	s_and_b32 s42, s12, s23
	s_lshl_b32 s12, s22, 11
	s_add_i32 s13, s13, 0xffff4000
	s_cmp_lt_i32 s22, 8
	s_cselect_b32 s56, s12, s13
	v_sub_u32_e64 v2, s42, 4 clamp
	s_sub_i32 s12, s56, s61
	v_readfirstlane_b32 s13, v2
	s_lshl_b32 s70, s52, 6
	s_ashr_i32 s53, s52, 31
	s_min_u32 s22, s13, s84
	v_add_u32_e32 v193, s12, v171
	s_ashr_i32 s71, s70, 31
	s_lshl_b64 s[12:13], s[52:53], 17
	s_ashr_i32 s57, s56, 31
	s_add_u32 s23, s91, s12
	s_addc_u32 s28, s92, s13
	s_lshl_b64 s[12:13], s[56:57], 2
	s_add_u32 s12, s23, s12
	s_addc_u32 s13, s28, s13
	s_cmp_eq_u32 s88, 4
	s_cbranch_scc0 .Lrk_skip
	s_lshl_b32 s98, s22, 8
	s_add_u32 s98, s98, 0x100000
	s_mov_b32 s99, 0
	v_mov_b32_e32 v248, v136
	v_mov_b32_e32 v249, 0
	v_lshl_add_u64 v[248:249], s[12:13], 0, v[248:249]
	v_lshl_add_u64 v[248:249], v[248:249], 0, s[98:99]
	global_load_dword v240, v[248:249], off
	global_load_dword v241, v[248:249], off offset:256
	global_load_dword v242, v[248:249], off offset:512
	global_load_dword v243, v[248:249], off offset:768
	global_load_dword v244, v[248:249], off offset:1024
	global_load_dword v245, v[248:249], off offset:1280
	global_load_dword v246, v[248:249], off offset:1536
	global_load_dword v247, v[248:249], off offset:1792
.Lrk_skip:
	s_lshl_b32 s28, s22, 6
	s_mul_i32 s23, s22, 57
	v_add_u32_e32 v4, s28, v193
	s_lshr_b32 s23, s23, 9
	v_ashrrev_i32_e32 v5, 31, v4
	s_mul_i32 s23, s23, 9
	v_lshlrev_b64 v[4:5], 12, v[4:5]
	s_sub_i32 s23, s22, s23
	v_lshl_add_u64 v[4:5], s[24:25], 0, v[4:5]
	s_and_b32 s23, s23, 0xff
	v_lshl_add_u64 v[4:5], s[70:71], 1, v[4:5]
	v_mov_b32_e32 v139, v3
	v_lshl_add_u64 v[4:5], v[4:5], 0, v[138:139]
	s_lshl_b32 s40, s23, 13
	v_lshl_add_u64 v[34:35], v[4:5], 0, s[18:19]
	s_add_i32 m0, s95, s40
	v_lshl_add_u64 v[4:5], v[4:5], 0, s[20:21]
	global_load_lds_dwordx4 v[34:35], off
	s_add_i32 m0, s96, s40
	v_mov_b32_e32 v137, v3
	global_load_lds_dwordx4 v[4:5], off
	v_lshl_add_u64 v[4:5], s[12:13], 0, v[136:137]
	v_cndmask_b32_e64 v2, 0, 1, s[30:31]
	s_mov_b64 s[40:41], 0x100000
	v_cmp_ne_u32_e64 s[12:13], 1, v2
	s_andn2_b64 vcc, exec, s[30:31]
	v_lshl_add_u64 v[142:143], v[4:5], 0, s[40:41]
	s_cbranch_vccnz .LBB0_240
	s_lshl_b32 s28, s28, 2
	v_lshl_add_u64 v[4:5], v[142:143], 0, s[28:29]
	s_waitcnt vmcnt(2)
	v_fmamk_f32 v2, v240, 0x3c800000, v191
	v_mul_f32_e32 v4, 0x4b800000, v2
	v_cmp_gt_f32_e32 vcc, s14, v2
	s_nop 1
	v_cndmask_b32_e32 v2, v2, v4, vcc
	v_rsq_f32_e32 v2, v2
	s_nop 0
	v_mul_f32_e32 v4, 0x45800000, v2
	v_cndmask_b32_e32 v2, v2, v4, vcc
	v_mul_f32_e32 v2, 0x3fb8aa3b, v2
	v_lshl_add_u32 v4, s23, 8, v172
	ds_write_b32 v4, v2
.LBB0_240:
	s_or_b32 s28, s22, 1
	s_mul_i32 s23, s28, 57
	s_lshr_b32 s23, s23, 9
	s_mul_i32 s23, s23, 9
	s_sub_i32 s23, s28, s23
	s_lshl_b32 s28, s28, 6
	v_add_u32_e32 v4, s28, v193
	v_ashrrev_i32_e32 v5, 31, v4
	v_lshlrev_b64 v[4:5], 12, v[4:5]
	v_lshl_add_u64 v[4:5], s[24:25], 0, v[4:5]
	s_and_b32 s23, s23, 0xff
	v_lshl_add_u64 v[4:5], s[70:71], 1, v[4:5]
	v_lshl_add_u64 v[4:5], v[4:5], 0, v[138:139]
	s_lshl_b32 s40, s23, 13
	v_lshl_add_u64 v[34:35], v[4:5], 0, s[18:19]
	s_add_i32 m0, s95, s40
	v_lshl_add_u64 v[4:5], v[4:5], 0, s[20:21]
	global_load_lds_dwordx4 v[34:35], off
	s_add_i32 m0, s96, s40
	s_and_b64 vcc, exec, s[12:13]
	global_load_lds_dwordx4 v[4:5], off
	s_cbranch_vccnz .LBB0_242
	s_lshl_b32 s28, s28, 2
	v_lshl_add_u64 v[4:5], v[142:143], 0, s[28:29]
	v_fmamk_f32 v2, v241, 0x3c800000, v191
	v_mul_f32_e32 v4, 0x4b800000, v2
	v_cmp_gt_f32_e32 vcc, s14, v2
	s_nop 1
	v_cndmask_b32_e32 v2, v2, v4, vcc
	v_rsq_f32_e32 v2, v2
	s_nop 0
	v_mul_f32_e32 v4, 0x45800000, v2
	v_cndmask_b32_e32 v2, v2, v4, vcc
	v_mul_f32_e32 v2, 0x3fb8aa3b, v2
	v_lshl_add_u32 v4, s23, 8, v172
	ds_write_b32 v4, v2
.LBB0_242:
	s_or_b32 s28, s22, 2
	s_mul_i32 s23, s28, 57
	s_lshr_b32 s23, s23, 9
	s_mul_i32 s23, s23, 9
	s_sub_i32 s23, s28, s23
	s_lshl_b32 s28, s28, 6
	v_add_u32_e32 v4, s28, v193
	v_ashrrev_i32_e32 v5, 31, v4
	v_lshlrev_b64 v[4:5], 12, v[4:5]
	v_lshl_add_u64 v[4:5], s[24:25], 0, v[4:5]
	s_and_b32 s23, s23, 0xff
	v_lshl_add_u64 v[4:5], s[70:71], 1, v[4:5]
	v_mov_b32_e32 v139, v3
	v_lshl_add_u64 v[4:5], v[4:5], 0, v[138:139]
	s_lshl_b32 s40, s23, 13
	v_lshl_add_u64 v[34:35], v[4:5], 0, s[18:19]
	s_add_i32 m0, s95, s40
	v_lshl_add_u64 v[4:5], v[4:5], 0, s[20:21]
	global_load_lds_dwordx4 v[34:35], off
	s_add_i32 m0, s96, s40
	s_and_b64 vcc, exec, s[12:13]
	global_load_lds_dwordx4 v[4:5], off
	s_cbranch_vccnz .LBB0_244
	s_lshl_b32 s28, s28, 2
	v_lshl_add_u64 v[4:5], v[142:143], 0, s[28:29]
	v_fmamk_f32 v2, v242, 0x3c800000, v191
	v_mul_f32_e32 v4, 0x4b800000, v2
	v_cmp_gt_f32_e32 vcc, s14, v2
	s_nop 1
	v_cndmask_b32_e32 v2, v2, v4, vcc
	v_rsq_f32_e32 v2, v2
	s_nop 0
	v_mul_f32_e32 v4, 0x45800000, v2
	v_cndmask_b32_e32 v2, v2, v4, vcc
	v_mul_f32_e32 v2, 0x3fb8aa3b, v2
	v_lshl_add_u32 v4, s23, 8, v172
	ds_write_b32 v4, v2
; __global__ void __launch_bounds__(NWAVES * 64, 2) fwd(Args a) {
;     ...
;             { const int lo0 = min(max(r0 - 4, 0), rows - 8);
;               for (int kr = lo0; kr < lo0 + 8; ++kr) STAGE_ROW(kr); }
.LBB0_244:
	s_or_b32 s28, s22, 3
	s_mul_i32 s23, s28, 57
	s_lshr_b32 s23, s23, 9
	s_mul_i32 s23, s23, 9
	s_sub_i32 s23, s28, s23
	s_lshl_b32 s28, s28, 6
	v_add_u32_e32 v4, s28, v193
	v_ashrrev_i32_e32 v5, 31, v4
	v_lshlrev_b64 v[4:5], 12, v[4:5]
	v_lshl_add_u64 v[4:5], s[24:25], 0, v[4:5]
	s_and_b32 s23, s23, 0xff
	v_lshl_add_u64 v[4:5], s[70:71], 1, v[4:5]
	v_lshl_add_u64 v[4:5], v[4:5], 0, v[138:139]
	s_lshl_b32 s40, s23, 13
	v_lshl_add_u64 v[34:35], v[4:5], 0, s[18:19]
	s_add_i32 m0, s95, s40
	v_lshl_add_u64 v[4:5], v[4:5], 0, s[20:21]
	global_load_lds_dwordx4 v[34:35], off
	s_add_i32 m0, s96, s40
	s_and_b64 vcc, exec, s[12:13]
	global_load_lds_dwordx4 v[4:5], off
	s_cbranch_vccnz .LBB0_246
	s_lshl_b32 s28, s28, 2
	v_lshl_add_u64 v[4:5], v[142:143], 0, s[28:29]
	v_fmamk_f32 v2, v243, 0x3c800000, v191
	v_mul_f32_e32 v4, 0x4b800000, v2
	v_cmp_gt_f32_e32 vcc, s14, v2
	s_nop 1
	v_cndmask_b32_e32 v2, v2, v4, vcc
	v_rsq_f32_e32 v2, v2
	s_nop 0
	v_mul_f32_e32 v4, 0x45800000, v2
	v_cndmask_b32_e32 v2, v2, v4, vcc
	v_mul_f32_e32 v2, 0x3fb8aa3b, v2
	v_lshl_add_u32 v4, s23, 8, v172
	ds_write_b32 v4, v2
.LBB0_246:
	s_add_i32 s28, s22, 4
	s_mul_i32 s23, s28, 57
	s_lshr_b32 s23, s23, 9
	s_mul_i32 s23, s23, 9
	s_sub_i32 s23, s28, s23
	s_lshl_b32 s28, s28, 6
	v_add_u32_e32 v4, s28, v193
	v_ashrrev_i32_e32 v5, 31, v4
	v_lshlrev_b64 v[4:5], 12, v[4:5]
	v_lshl_add_u64 v[4:5], s[24:25], 0, v[4:5]
	s_and_b32 s23, s23, 0xff
	v_lshl_add_u64 v[4:5], s[70:71], 1, v[4:5]
	v_mov_b32_e32 v139, v3
	v_lshl_add_u64 v[4:5], v[4:5], 0, v[138:139]
	s_lshl_b32 s40, s23, 13
	v_lshl_add_u64 v[34:35], v[4:5], 0, s[18:19]
	s_add_i32 m0, s95, s40
	v_lshl_add_u64 v[4:5], v[4:5], 0, s[20:21]
	global_load_lds_dwordx4 v[34:35], off
	s_add_i32 m0, s96, s40
	s_and_b64 vcc, exec, s[12:13]
	global_load_lds_dwordx4 v[4:5], off
	s_cbranch_vccnz .LBB0_248
	s_lshl_b32 s28, s28, 2
	v_lshl_add_u64 v[4:5], v[142:143], 0, s[28:29]
	v_fmamk_f32 v2, v244, 0x3c800000, v191
	v_mul_f32_e32 v4, 0x4b800000, v2
	v_cmp_gt_f32_e32 vcc, s14, v2
	s_nop 1
	v_cndmask_b32_e32 v2, v2, v4, vcc
	v_rsq_f32_e32 v2, v2
	s_nop 0
	v_mul_f32_e32 v4, 0x45800000, v2
	v_cndmask_b32_e32 v2, v2, v4, vcc
	v_mul_f32_e32 v2, 0x3fb8aa3b, v2
	v_lshl_add_u32 v4, s23, 8, v172
	ds_write_b32 v4, v2
.LBB0_248:
	s_add_i32 s28, s22, 5
	s_mul_i32 s23, s28, 57
	s_lshr_b32 s23, s23, 9
	s_mul_i32 s23, s23, 9
	s_sub_i32 s23, s28, s23
	s_lshl_b32 s28, s28, 6
	v_add_u32_e32 v4, s28, v193
	v_ashrrev_i32_e32 v5, 31, v4
	v_lshlrev_b64 v[4:5], 12, v[4:5]
	v_lshl_add_u64 v[4:5], s[24:25], 0, v[4:5]
	s_and_b32 s23, s23, 0xff
	v_lshl_add_u64 v[4:5], s[70:71], 1, v[4:5]
	v_lshl_add_u64 v[4:5], v[4:5], 0, v[138:139]
	s_lshl_b32 s40, s23, 13
	v_lshl_add_u64 v[34:35], v[4:5], 0, s[18:19]
	s_add_i32 m0, s95, s40
	v_lshl_add_u64 v[4:5], v[4:5], 0, s[20:21]
	global_load_lds_dwordx4 v[34:35], off
	s_add_i32 m0, s96, s40
	s_and_b64 vcc, exec, s[12:13]
	global_load_lds_dwordx4 v[4:5], off
	s_cbranch_vccnz .LBB0_250
	s_lshl_b32 s28, s28, 2
	v_lshl_add_u64 v[4:5], v[142:143], 0, s[28:29]
	v_fmamk_f32 v2, v245, 0x3c800000, v191
	v_mul_f32_e32 v4, 0x4b800000, v2
	v_cmp_gt_f32_e32 vcc, s14, v2
	s_nop 1
	v_cndmask_b32_e32 v2, v2, v4, vcc
	v_rsq_f32_e32 v2, v2
	s_nop 0
	v_mul_f32_e32 v4, 0x45800000, v2
	v_cndmask_b32_e32 v2, v2, v4, vcc
	v_mul_f32_e32 v2, 0x3fb8aa3b, v2
	v_lshl_add_u32 v4, s23, 8, v172
	ds_write_b32 v4, v2
.LBB0_250:
	s_add_i32 s28, s22, 6
	s_mul_i32 s23, s28, 57
	s_lshr_b32 s23, s23, 9
	s_mul_i32 s23, s23, 9
	s_sub_i32 s23, s28, s23
	s_lshl_b32 s28, s28, 6
	v_add_u32_e32 v4, s28, v193
	v_ashrrev_i32_e32 v5, 31, v4
	v_lshlrev_b64 v[4:5], 12, v[4:5]
	v_lshl_add_u64 v[4:5], s[24:25], 0, v[4:5]
	s_and_b32 s23, s23, 0xff
	v_lshl_add_u64 v[4:5], s[70:71], 1, v[4:5]
	v_mov_b32_e32 v139, v3
	v_lshl_add_u64 v[4:5], v[4:5], 0, v[138:139]
	s_lshl_b32 s40, s23, 13
	v_lshl_add_u64 v[34:35], v[4:5], 0, s[18:19]
	s_add_i32 m0, s95, s40
	v_lshl_add_u64 v[4:5], v[4:5], 0, s[20:21]
	global_load_lds_dwordx4 v[34:35], off
	s_add_i32 m0, s96, s40
	s_and_b64 vcc, exec, s[12:13]
	global_load_lds_dwordx4 v[4:5], off
	s_cbranch_vccnz .LBB0_252
	s_lshl_b32 s28, s28, 2
	v_lshl_add_u64 v[4:5], v[142:143], 0, s[28:29]
	v_fmamk_f32 v2, v246, 0x3c800000, v191
	v_mul_f32_e32 v4, 0x4b800000, v2
	v_cmp_gt_f32_e32 vcc, s14, v2
	s_nop 1
	v_cndmask_b32_e32 v2, v2, v4, vcc
	v_rsq_f32_e32 v2, v2
	s_nop 0
	v_mul_f32_e32 v4, 0x45800000, v2
	v_cndmask_b32_e32 v2, v2, v4, vcc
	v_mul_f32_e32 v2, 0x3fb8aa3b, v2
	v_lshl_add_u32 v4, s23, 8, v172
	ds_write_b32 v4, v2
.LBB0_252:
	s_add_i32 s23, s22, 7
	s_mul_i32 s22, s23, 57
	s_lshr_b32 s22, s22, 9
	s_mul_i32 s22, s22, 9
	s_sub_i32 s22, s23, s22
	s_lshl_b32 s23, s23, 6
	v_add_u32_e32 v4, s23, v193
	v_ashrrev_i32_e32 v5, 31, v4
	v_lshlrev_b64 v[4:5], 12, v[4:5]
	v_lshl_add_u64 v[4:5], s[24:25], 0, v[4:5]
	s_and_b32 s22, s22, 0xff
	v_lshl_add_u64 v[4:5], s[70:71], 1, v[4:5]
	v_lshl_add_u64 v[4:5], v[4:5], 0, v[138:139]
	s_lshl_b32 s28, s22, 13
	v_lshl_add_u64 v[34:35], v[4:5], 0, s[18:19]
	s_add_i32 m0, s95, s28
	v_lshl_add_u64 v[4:5], v[4:5], 0, s[20:21]
	global_load_lds_dwordx4 v[34:35], off
	s_add_i32 m0, s96, s28
	s_and_b64 vcc, exec, s[12:13]
	global_load_lds_dwordx4 v[4:5], off
	s_cbranch_vccnz .LBB0_254
	s_lshl_b32 s28, s23, 2
	v_lshl_add_u64 v[4:5], v[142:143], 0, s[28:29]
	v_fmamk_f32 v2, v247, 0x3c800000, v191
	v_mul_f32_e32 v4, 0x4b800000, v2
	v_cmp_gt_f32_e32 vcc, s14, v2
	s_nop 1
	v_cndmask_b32_e32 v2, v2, v4, vcc
	v_rsq_f32_e32 v2, v2
	s_nop 0
	v_mul_f32_e32 v4, 0x45800000, v2
	v_cndmask_b32_e32 v2, v2, v4, vcc
	v_mul_f32_e32 v2, 0x3fb8aa3b, v2
	v_lshl_add_u32 v4, s22, 8, v172
	ds_write_b32 v4, v2
